# last-unit write-through epilogue also in the merge GEMM
# speedup vs baseline: 1.0009x; 1.0009x over previous
.LBB0_1017:
	s_and_b64 vcc, exec, s[36:37]
	s_cbranch_vccz .Llast_mrg
	v_readlane_b32 s2, v251, 1
	v_readlane_b32 s3, v251, 2
	v_readlane_b32 s16, v246, 19
	v_add_u32_e32 v2, 0x100, v164
	v_add_u32_e32 v4, 0x10000, v164
	v_add_u32_e32 v5, 0x10100, v164
	s_nop 0
	global_load_dwordx4 v[134:137], v164, s[2:3]
	global_load_dwordx4 v[158:161], v5, s[2:3]
	global_load_dwordx4 v[138:141], v2, s[2:3]
	global_load_dwordx4 v[142:145], v4, s[2:3]
	v_add_u32_e32 v165, 0x20000, v164
	v_add_u32_e32 v166, 0x20100, v164
	v_add_u32_e32 v167, 0x30000, v164
	v_add_u32_e32 v196, 0x30100, v164
	global_load_dwordx4 v[180:183], v165, s[2:3]
	global_load_dwordx4 v[184:187], v166, s[2:3]
	global_load_dwordx4 v[188:191], v167, s[2:3]
	global_load_dwordx4 v[192:195], v196, s[2:3]
	v_readlane_b32 s17, v246, 20
	s_andn2_b64 vcc, exec, s[36:37]
	s_waitcnt vmcnt(0)
	v_lshlrev_b32_e32 v197, 16, v134
	v_and_b32_e32 v134, 0xffff0000, v134
	v_lshlrev_b32_e32 v198, 16, v135
	v_and_b32_e32 v135, 0xffff0000, v135
	v_lshlrev_b32_e32 v199, 16, v136
	v_lshlrev_b32_e32 v207, 16, v137
	v_and_b32_e32 v137, 0xffff0000, v137
	v_and_b32_e32 v136, 0xffff0000, v136
	v_mul_f32_e32 v130, v130, v197
	v_mul_f32_e32 v131, v131, v134
	v_mul_f32_e32 v132, v132, v198
	v_mul_f32_e32 v133, v133, v135
	v_mul_f32_e32 v134, v126, v199
	v_mul_f32_e32 v129, v129, v137
	v_lshlrev_b32_e32 v137, 16, v138
	v_and_b32_e32 v138, 0xffff0000, v138
	v_lshlrev_b32_e32 v197, 16, v139
	v_and_b32_e32 v139, 0xffff0000, v139
	v_lshlrev_b32_e32 v198, 16, v140
	v_and_b32_e32 v140, 0xffff0000, v140
	v_lshlrev_b32_e32 v199, 16, v141
	v_and_b32_e32 v141, 0xffff0000, v141
	v_lshlrev_b32_e32 v209, 16, v144
	v_and_b32_e32 v144, 0xffff0000, v144
	v_lshlrev_b32_e32 v210, 16, v145
	v_and_b32_e32 v145, 0xffff0000, v145
	v_lshlrev_b32_e32 v211, 16, v158
	v_and_b32_e32 v158, 0xffff0000, v158
	v_lshlrev_b32_e32 v212, 16, v159
	v_and_b32_e32 v159, 0xffff0000, v159
	v_mul_f32_e32 v135, v127, v136
	v_mul_f32_e32 v136, v128, v207
	v_lshlrev_b32_e32 v207, 16, v142
	v_and_b32_e32 v142, 0xffff0000, v142
	v_lshlrev_b32_e32 v208, 16, v143
	v_and_b32_e32 v143, 0xffff0000, v143
	v_cvt_pk_bf16_f32 v126, v130, v131
	v_cvt_pk_bf16_f32 v127, v132, v133
	v_cvt_pk_bf16_f32 v128, v134, v135
	v_cvt_pk_bf16_f32 v129, v136, v129
	v_mul_f32_e32 v122, v122, v137
	v_mul_f32_e32 v123, v123, v138
	v_mul_f32_e32 v124, v124, v197
	v_mul_f32_e32 v125, v125, v139
	v_mul_f32_e32 v114, v114, v198
	v_mul_f32_e32 v115, v115, v140
	v_mul_f32_e32 v116, v116, v199
	v_mul_f32_e32 v117, v117, v141
	v_mul_f32_e32 v130, v110, v209
	v_mul_f32_e32 v131, v111, v144
	v_mul_f32_e32 v132, v112, v210
	v_mul_f32_e32 v133, v113, v145
	v_mul_f32_e32 v106, v106, v211
	v_mul_f32_e32 v107, v107, v158
	global_store_dwordx4 v164, v[126:129], s[16:17]
	v_cvt_pk_bf16_f32 v110, v122, v123
	v_cvt_pk_bf16_f32 v111, v124, v125
	v_cvt_pk_bf16_f32 v112, v114, v115
	v_cvt_pk_bf16_f32 v113, v116, v117
	global_store_dwordx4 v2, v[110:113], s[16:17]
	v_mul_f32_e32 v2, v109, v159
	v_mul_f32_e32 v118, v118, v207
	v_mul_f32_e32 v119, v119, v142
	v_mul_f32_e32 v120, v120, v208
	v_mul_f32_e32 v121, v121, v143
	v_mul_f32_e32 v108, v108, v212
	v_cvt_pk_bf16_f32 v110, v118, v119
	v_cvt_pk_bf16_f32 v111, v120, v121
	v_cvt_pk_bf16_f32 v112, v130, v131
	v_cvt_pk_bf16_f32 v113, v132, v133
	global_store_dwordx4 v4, v[110:113], s[16:17]
	v_cvt_pk_bf16_f32 v106, v106, v107
	v_cvt_pk_bf16_f32 v107, v108, v2
	v_lshlrev_b32_e32 v2, 16, v160
	v_and_b32_e32 v4, 0xffff0000, v160
	v_mul_f32_e32 v2, v102, v2
	v_mul_f32_e32 v4, v103, v4
	v_cvt_pk_bf16_f32 v108, v2, v4
	v_lshlrev_b32_e32 v2, 16, v161
	v_and_b32_e32 v4, 0xffff0000, v161
	v_mul_f32_e32 v2, v104, v2
	v_mul_f32_e32 v4, v105, v4
	v_cvt_pk_bf16_f32 v109, v2, v4
	v_lshlrev_b32_e32 v2, 16, v180
	v_and_b32_e32 v4, 0xffff0000, v180
	v_mul_f32_e32 v2, v98, v2
	v_mul_f32_e32 v4, v99, v4
	global_store_dwordx4 v5, v[106:109], s[16:17]
	v_cvt_pk_bf16_f32 v98, v2, v4
	v_lshlrev_b32_e32 v2, 16, v181
	v_and_b32_e32 v4, 0xffff0000, v181
	v_mul_f32_e32 v2, v100, v2
	v_mul_f32_e32 v4, v101, v4
	v_cvt_pk_bf16_f32 v99, v2, v4
	v_lshlrev_b32_e32 v2, 16, v182
	v_and_b32_e32 v4, 0xffff0000, v182
	v_mul_f32_e32 v2, v94, v2
	v_mul_f32_e32 v4, v95, v4
	v_cvt_pk_bf16_f32 v100, v2, v4
	v_lshlrev_b32_e32 v2, 16, v183
	v_and_b32_e32 v4, 0xffff0000, v183
	v_mul_f32_e32 v2, v96, v2
	v_mul_f32_e32 v4, v97, v4
	v_cvt_pk_bf16_f32 v101, v2, v4
	v_lshlrev_b32_e32 v2, 16, v184
	v_and_b32_e32 v4, 0xffff0000, v184
	v_mul_f32_e32 v2, v90, v2
	v_mul_f32_e32 v4, v91, v4
	global_store_dwordx4 v165, v[98:101], s[16:17]
	v_cvt_pk_bf16_f32 v90, v2, v4
	v_lshlrev_b32_e32 v2, 16, v185
	v_and_b32_e32 v4, 0xffff0000, v185
	v_mul_f32_e32 v2, v92, v2
	v_mul_f32_e32 v4, v93, v4
	v_cvt_pk_bf16_f32 v91, v2, v4
	v_lshlrev_b32_e32 v2, 16, v186
	v_and_b32_e32 v4, 0xffff0000, v186
	v_mul_f32_e32 v2, v86, v2
	v_mul_f32_e32 v4, v87, v4
	v_cvt_pk_bf16_f32 v92, v2, v4
	v_lshlrev_b32_e32 v2, 16, v187
	v_and_b32_e32 v4, 0xffff0000, v187
	v_mul_f32_e32 v2, v88, v2
	v_mul_f32_e32 v4, v89, v4
	v_cvt_pk_bf16_f32 v93, v2, v4
	v_lshlrev_b32_e32 v2, 16, v188
	v_and_b32_e32 v4, 0xffff0000, v188
	v_mul_f32_e32 v2, v82, v2
	v_mul_f32_e32 v4, v83, v4
	global_store_dwordx4 v166, v[90:93], s[16:17]
	v_cvt_pk_bf16_f32 v82, v2, v4
	v_lshlrev_b32_e32 v2, 16, v189
	v_and_b32_e32 v4, 0xffff0000, v189
	v_mul_f32_e32 v2, v84, v2
	v_mul_f32_e32 v4, v85, v4
	v_cvt_pk_bf16_f32 v83, v2, v4
	v_lshlrev_b32_e32 v2, 16, v190
	v_and_b32_e32 v4, 0xffff0000, v190
	v_mul_f32_e32 v2, v78, v2
	v_mul_f32_e32 v4, v79, v4
	v_cvt_pk_bf16_f32 v84, v2, v4
	v_lshlrev_b32_e32 v2, 16, v191
	v_and_b32_e32 v4, 0xffff0000, v191
	v_mul_f32_e32 v2, v80, v2
	v_mul_f32_e32 v4, v81, v4
	v_cvt_pk_bf16_f32 v85, v2, v4
	v_lshlrev_b32_e32 v2, 16, v192
	v_and_b32_e32 v4, 0xffff0000, v192
	v_mul_f32_e32 v2, v74, v2
	v_mul_f32_e32 v4, v75, v4
	global_store_dwordx4 v167, v[82:85], s[16:17]
	v_cvt_pk_bf16_f32 v74, v2, v4
	v_lshlrev_b32_e32 v2, 16, v193
	v_and_b32_e32 v4, 0xffff0000, v193
	v_mul_f32_e32 v2, v76, v2
	v_mul_f32_e32 v4, v77, v4
	v_cvt_pk_bf16_f32 v75, v2, v4
	v_lshlrev_b32_e32 v2, 16, v194
	v_and_b32_e32 v4, 0xffff0000, v194
	v_mul_f32_e32 v2, v70, v2
	v_mul_f32_e32 v4, v71, v4
	v_cvt_pk_bf16_f32 v76, v2, v4
	v_lshlrev_b32_e32 v2, 16, v195
	v_and_b32_e32 v4, 0xffff0000, v195
	v_mul_f32_e32 v2, v72, v2
	v_mul_f32_e32 v4, v73, v4
	v_cvt_pk_bf16_f32 v77, v2, v4
	global_store_dwordx4 v196, v[74:77], s[16:17]
	v_add_u32_e32 v2, 0x80000, v164
	global_load_dwordx4 v[70:73], v2, s[2:3]
	v_add_u32_e32 v4, 0x80100, v164
	global_load_dwordx4 v[74:77], v4, s[2:3]
	v_add_u32_e32 v5, 0x90000, v164
	global_load_dwordx4 v[78:81], v5, s[2:3]
	v_add_u32_e32 v102, 0x90100, v164
	global_load_dwordx4 v[82:85], v102, s[2:3]
	v_add_u32_e32 v103, 0xa0000, v164
	v_add_u32_e32 v104, 0xa0100, v164
	global_load_dwordx4 v[86:89], v103, s[2:3]
	global_load_dwordx4 v[90:93], v104, s[2:3]
	v_add_u32_e32 v105, 0xb0000, v164
	v_add_u32_e32 v106, 0xb0100, v164
	global_load_dwordx4 v[94:97], v105, s[2:3]
	global_load_dwordx4 v[98:101], v106, s[2:3]
	s_waitcnt vmcnt(7)
	v_lshlrev_b32_e32 v107, 16, v70
	v_and_b32_e32 v70, 0xffff0000, v70
	v_mul_f32_e32 v66, v66, v107
	v_mul_f32_e32 v67, v67, v70
	v_cvt_pk_bf16_f32 v66, v66, v67
	v_lshlrev_b32_e32 v67, 16, v71
	v_mul_f32_e32 v67, v68, v67
	v_and_b32_e32 v68, 0xffff0000, v71
	v_mul_f32_e32 v68, v69, v68
	v_cvt_pk_bf16_f32 v67, v67, v68
	v_lshlrev_b32_e32 v68, 16, v72
	v_mul_f32_e32 v62, v62, v68
	v_and_b32_e32 v68, 0xffff0000, v72
	v_mul_f32_e32 v63, v63, v68
	v_cvt_pk_bf16_f32 v68, v62, v63
	v_lshlrev_b32_e32 v62, 16, v73
	v_and_b32_e32 v63, 0xffff0000, v73
	v_mul_f32_e32 v62, v64, v62
	v_mul_f32_e32 v63, v65, v63
	v_cvt_pk_bf16_f32 v69, v62, v63
	global_store_dwordx4 v2, v[66:69], s[16:17]
	s_waitcnt vmcnt(7)
	v_lshlrev_b32_e32 v2, 16, v74
	v_mul_f32_e32 v2, v58, v2
	v_and_b32_e32 v58, 0xffff0000, v74
	v_mul_f32_e32 v58, v59, v58
	v_cvt_pk_bf16_f32 v58, v2, v58
	v_lshlrev_b32_e32 v2, 16, v75
	v_and_b32_e32 v59, 0xffff0000, v75
	v_mul_f32_e32 v2, v60, v2
	v_mul_f32_e32 v59, v61, v59
	v_cvt_pk_bf16_f32 v59, v2, v59
	v_lshlrev_b32_e32 v2, 16, v76
	v_mul_f32_e32 v2, v54, v2
	v_and_b32_e32 v54, 0xffff0000, v76
	v_mul_f32_e32 v54, v55, v54
	v_cvt_pk_bf16_f32 v60, v2, v54
	v_lshlrev_b32_e32 v2, 16, v77
	v_mul_f32_e32 v2, v56, v2
	v_and_b32_e32 v54, 0xffff0000, v77
	v_mul_f32_e32 v54, v57, v54
	v_cvt_pk_bf16_f32 v61, v2, v54
	global_store_dwordx4 v4, v[58:61], s[16:17]
	s_waitcnt vmcnt(7)
	v_lshlrev_b32_e32 v2, 16, v78
	v_and_b32_e32 v4, 0xffff0000, v78
	v_mul_f32_e32 v2, v50, v2
	v_mul_f32_e32 v4, v51, v4
	v_cvt_pk_bf16_f32 v50, v2, v4
	v_lshlrev_b32_e32 v2, 16, v79
	v_and_b32_e32 v4, 0xffff0000, v79
	v_mul_f32_e32 v2, v52, v2
	v_mul_f32_e32 v4, v53, v4
	v_cvt_pk_bf16_f32 v51, v2, v4
	v_lshlrev_b32_e32 v2, 16, v80
	v_and_b32_e32 v4, 0xffff0000, v80
	v_mul_f32_e32 v2, v46, v2
	v_mul_f32_e32 v4, v47, v4
	v_cvt_pk_bf16_f32 v52, v2, v4
	v_lshlrev_b32_e32 v2, 16, v81
	v_and_b32_e32 v4, 0xffff0000, v81
	v_mul_f32_e32 v2, v48, v2
	v_mul_f32_e32 v4, v49, v4
	v_cvt_pk_bf16_f32 v53, v2, v4
	s_waitcnt vmcnt(6)
	v_lshlrev_b32_e32 v2, 16, v82
	v_and_b32_e32 v4, 0xffff0000, v82
	v_mul_f32_e32 v2, v42, v2
	v_mul_f32_e32 v4, v43, v4
	global_store_dwordx4 v5, v[50:53], s[16:17]
	v_cvt_pk_bf16_f32 v42, v2, v4
	v_lshlrev_b32_e32 v2, 16, v83
	v_and_b32_e32 v4, 0xffff0000, v83
	v_mul_f32_e32 v2, v44, v2
	v_mul_f32_e32 v4, v45, v4
	v_cvt_pk_bf16_f32 v43, v2, v4
	v_lshlrev_b32_e32 v2, 16, v84
	v_and_b32_e32 v4, 0xffff0000, v84
	v_mul_f32_e32 v2, v38, v2
	v_mul_f32_e32 v4, v39, v4
	v_cvt_pk_bf16_f32 v44, v2, v4
	v_lshlrev_b32_e32 v2, 16, v85
	v_and_b32_e32 v4, 0xffff0000, v85
	v_mul_f32_e32 v2, v40, v2
	v_mul_f32_e32 v4, v41, v4
	v_cvt_pk_bf16_f32 v45, v2, v4
	s_waitcnt vmcnt(6)
	v_lshlrev_b32_e32 v2, 16, v86
	v_and_b32_e32 v4, 0xffff0000, v86
	v_mul_f32_e32 v2, v34, v2
	v_mul_f32_e32 v4, v35, v4
	global_store_dwordx4 v102, v[42:45], s[16:17]
	v_cvt_pk_bf16_f32 v34, v2, v4
	v_lshlrev_b32_e32 v2, 16, v87
	v_and_b32_e32 v4, 0xffff0000, v87
	v_mul_f32_e32 v2, v36, v2
	v_mul_f32_e32 v4, v37, v4
	v_cvt_pk_bf16_f32 v35, v2, v4
	v_lshlrev_b32_e32 v2, 16, v88
	v_and_b32_e32 v4, 0xffff0000, v88
	v_mul_f32_e32 v2, v30, v2
	v_mul_f32_e32 v4, v31, v4
	v_cvt_pk_bf16_f32 v36, v2, v4
	v_lshlrev_b32_e32 v2, 16, v89
	v_and_b32_e32 v4, 0xffff0000, v89
	v_mul_f32_e32 v2, v32, v2
	v_mul_f32_e32 v4, v33, v4
	v_cvt_pk_bf16_f32 v37, v2, v4
	s_waitcnt vmcnt(6)
	v_lshlrev_b32_e32 v2, 16, v90
	v_and_b32_e32 v4, 0xffff0000, v90
	v_mul_f32_e32 v2, v26, v2
	v_mul_f32_e32 v4, v27, v4
	global_store_dwordx4 v103, v[34:37], s[16:17]
	v_cvt_pk_bf16_f32 v26, v2, v4
	v_lshlrev_b32_e32 v2, 16, v91
	v_and_b32_e32 v4, 0xffff0000, v91
	v_mul_f32_e32 v2, v28, v2
	v_mul_f32_e32 v4, v29, v4
	v_cvt_pk_bf16_f32 v27, v2, v4
	v_lshlrev_b32_e32 v2, 16, v92
	v_and_b32_e32 v4, 0xffff0000, v92
	v_mul_f32_e32 v2, v22, v2
	v_mul_f32_e32 v4, v23, v4
	v_cvt_pk_bf16_f32 v28, v2, v4
	v_lshlrev_b32_e32 v2, 16, v93
	v_and_b32_e32 v4, 0xffff0000, v93
	v_mul_f32_e32 v2, v24, v2
	v_mul_f32_e32 v4, v25, v4
	v_cvt_pk_bf16_f32 v29, v2, v4
	s_waitcnt vmcnt(6)
	v_lshlrev_b32_e32 v2, 16, v94
	v_and_b32_e32 v4, 0xffff0000, v94
	v_mul_f32_e32 v2, v18, v2
	v_mul_f32_e32 v4, v19, v4
	global_store_dwordx4 v104, v[26:29], s[16:17]
	v_cvt_pk_bf16_f32 v18, v2, v4
	v_lshlrev_b32_e32 v2, 16, v95
	v_and_b32_e32 v4, 0xffff0000, v95
	v_mul_f32_e32 v2, v20, v2
	v_mul_f32_e32 v4, v21, v4
	v_cvt_pk_bf16_f32 v19, v2, v4
	v_lshlrev_b32_e32 v2, 16, v96
	v_and_b32_e32 v4, 0xffff0000, v96
	v_mul_f32_e32 v2, v14, v2
	v_mul_f32_e32 v4, v15, v4
	v_cvt_pk_bf16_f32 v20, v2, v4
	v_lshlrev_b32_e32 v2, 16, v97
	v_and_b32_e32 v4, 0xffff0000, v97
	v_mul_f32_e32 v2, v16, v2
	v_mul_f32_e32 v4, v17, v4
	v_cvt_pk_bf16_f32 v21, v2, v4
	s_waitcnt vmcnt(6)
	v_lshlrev_b32_e32 v2, 16, v98
	v_and_b32_e32 v4, 0xffff0000, v98
	v_mul_f32_e32 v2, v10, v2
	v_mul_f32_e32 v4, v11, v4
	global_store_dwordx4 v105, v[18:21], s[16:17]
	v_cvt_pk_bf16_f32 v4, v2, v4
	v_lshlrev_b32_e32 v2, 16, v99
	v_and_b32_e32 v5, 0xffff0000, v99
	v_mul_f32_e32 v2, v12, v2
	v_mul_f32_e32 v5, v13, v5
	v_cvt_pk_bf16_f32 v5, v2, v5
	v_lshlrev_b32_e32 v2, 16, v100
	v_mul_f32_e32 v2, v6, v2
	v_and_b32_e32 v6, 0xffff0000, v100
	v_mul_f32_e32 v6, v7, v6
	v_and_b32_e32 v7, 0xffff0000, v101
	v_cvt_pk_bf16_f32 v6, v2, v6
	v_lshlrev_b32_e32 v2, 16, v101
	v_mul_f32_e32 v7, v9, v7
	v_mul_f32_e32 v2, v8, v2
	v_cvt_pk_bf16_f32 v7, v2, v7
	global_store_dwordx4 v106, v[4:7], s[16:17]
	s_mov_b64 s[16:17], -1
.Ljoin_mrg:
	s_cbranch_vccnz .LBB0_1008
	s_andn2_b64 vcc, exec, s[0:1]
	s_cbranch_vccnz .LBB0_1007
	s_barrier
	s_branch .LBB0_1007
.Llast_mrg:
	v_readlane_b32 s2, v251, 1
	v_readlane_b32 s3, v251, 2
	v_readlane_b32 s16, v246, 19
	v_add_u32_e32 v2, 0x100, v164
	v_add_u32_e32 v4, 0x10000, v164
	v_add_u32_e32 v5, 0x10100, v164
	s_nop 0
	global_load_dwordx4 v[134:137], v164, s[2:3]
	global_load_dwordx4 v[158:161], v5, s[2:3]
	global_load_dwordx4 v[138:141], v2, s[2:3]
	global_load_dwordx4 v[142:145], v4, s[2:3]
	v_add_u32_e32 v165, 0x20000, v164
	v_add_u32_e32 v166, 0x20100, v164
	v_add_u32_e32 v167, 0x30000, v164
	v_add_u32_e32 v196, 0x30100, v164
	global_load_dwordx4 v[180:183], v165, s[2:3]
	global_load_dwordx4 v[184:187], v166, s[2:3]
	global_load_dwordx4 v[188:191], v167, s[2:3]
	global_load_dwordx4 v[192:195], v196, s[2:3]
	v_readlane_b32 s17, v246, 20
	s_andn2_b64 vcc, exec, s[36:37]
	s_waitcnt vmcnt(0)
	v_lshlrev_b32_e32 v197, 16, v134
	v_and_b32_e32 v134, 0xffff0000, v134
	v_lshlrev_b32_e32 v198, 16, v135
	v_and_b32_e32 v135, 0xffff0000, v135
	v_lshlrev_b32_e32 v199, 16, v136
	v_lshlrev_b32_e32 v207, 16, v137
	v_and_b32_e32 v137, 0xffff0000, v137
	v_and_b32_e32 v136, 0xffff0000, v136
	v_mul_f32_e32 v130, v130, v197
	v_mul_f32_e32 v131, v131, v134
	v_mul_f32_e32 v132, v132, v198
	v_mul_f32_e32 v133, v133, v135
	v_mul_f32_e32 v134, v126, v199
	v_mul_f32_e32 v129, v129, v137
	v_lshlrev_b32_e32 v137, 16, v138
	v_and_b32_e32 v138, 0xffff0000, v138
	v_lshlrev_b32_e32 v197, 16, v139
	v_and_b32_e32 v139, 0xffff0000, v139
	v_lshlrev_b32_e32 v198, 16, v140
	v_and_b32_e32 v140, 0xffff0000, v140
	v_lshlrev_b32_e32 v199, 16, v141
	v_and_b32_e32 v141, 0xffff0000, v141
	v_lshlrev_b32_e32 v209, 16, v144
	v_and_b32_e32 v144, 0xffff0000, v144
	v_lshlrev_b32_e32 v210, 16, v145
	v_and_b32_e32 v145, 0xffff0000, v145
	v_lshlrev_b32_e32 v211, 16, v158
	v_and_b32_e32 v158, 0xffff0000, v158
	v_lshlrev_b32_e32 v212, 16, v159
	v_and_b32_e32 v159, 0xffff0000, v159
	v_mul_f32_e32 v135, v127, v136
	v_mul_f32_e32 v136, v128, v207
	v_lshlrev_b32_e32 v207, 16, v142
	v_and_b32_e32 v142, 0xffff0000, v142
	v_lshlrev_b32_e32 v208, 16, v143
	v_and_b32_e32 v143, 0xffff0000, v143
	v_cvt_pk_bf16_f32 v126, v130, v131
	v_cvt_pk_bf16_f32 v127, v132, v133
	v_cvt_pk_bf16_f32 v128, v134, v135
	v_cvt_pk_bf16_f32 v129, v136, v129
	v_mul_f32_e32 v122, v122, v137
	v_mul_f32_e32 v123, v123, v138
	v_mul_f32_e32 v124, v124, v197
	v_mul_f32_e32 v125, v125, v139
	v_mul_f32_e32 v114, v114, v198
	v_mul_f32_e32 v115, v115, v140
	v_mul_f32_e32 v116, v116, v199
	v_mul_f32_e32 v117, v117, v141
	v_mul_f32_e32 v130, v110, v209
	v_mul_f32_e32 v131, v111, v144
	v_mul_f32_e32 v132, v112, v210
	v_mul_f32_e32 v133, v113, v145
	v_mul_f32_e32 v106, v106, v211
	v_mul_f32_e32 v107, v107, v158
	global_store_dwordx4 v164, v[126:129], s[16:17] sc0 sc1
	v_cvt_pk_bf16_f32 v110, v122, v123
	v_cvt_pk_bf16_f32 v111, v124, v125
	v_cvt_pk_bf16_f32 v112, v114, v115
	v_cvt_pk_bf16_f32 v113, v116, v117
	global_store_dwordx4 v2, v[110:113], s[16:17] sc0 sc1
	v_mul_f32_e32 v2, v109, v159
	v_mul_f32_e32 v118, v118, v207
	v_mul_f32_e32 v119, v119, v142
	v_mul_f32_e32 v120, v120, v208
	v_mul_f32_e32 v121, v121, v143
	v_mul_f32_e32 v108, v108, v212
	v_cvt_pk_bf16_f32 v110, v118, v119
	v_cvt_pk_bf16_f32 v111, v120, v121
	v_cvt_pk_bf16_f32 v112, v130, v131
	v_cvt_pk_bf16_f32 v113, v132, v133
	global_store_dwordx4 v4, v[110:113], s[16:17] sc0 sc1
	v_cvt_pk_bf16_f32 v106, v106, v107
	v_cvt_pk_bf16_f32 v107, v108, v2
	v_lshlrev_b32_e32 v2, 16, v160
	v_and_b32_e32 v4, 0xffff0000, v160
	v_mul_f32_e32 v2, v102, v2
	v_mul_f32_e32 v4, v103, v4
	v_cvt_pk_bf16_f32 v108, v2, v4
	v_lshlrev_b32_e32 v2, 16, v161
	v_and_b32_e32 v4, 0xffff0000, v161
	v_mul_f32_e32 v2, v104, v2
	v_mul_f32_e32 v4, v105, v4
	v_cvt_pk_bf16_f32 v109, v2, v4
	v_lshlrev_b32_e32 v2, 16, v180
	v_and_b32_e32 v4, 0xffff0000, v180
	v_mul_f32_e32 v2, v98, v2
	v_mul_f32_e32 v4, v99, v4
	global_store_dwordx4 v5, v[106:109], s[16:17] sc0 sc1
	v_cvt_pk_bf16_f32 v98, v2, v4
	v_lshlrev_b32_e32 v2, 16, v181
	v_and_b32_e32 v4, 0xffff0000, v181
	v_mul_f32_e32 v2, v100, v2
	v_mul_f32_e32 v4, v101, v4
	v_cvt_pk_bf16_f32 v99, v2, v4
	v_lshlrev_b32_e32 v2, 16, v182
	v_and_b32_e32 v4, 0xffff0000, v182
	v_mul_f32_e32 v2, v94, v2
	v_mul_f32_e32 v4, v95, v4
	v_cvt_pk_bf16_f32 v100, v2, v4
	v_lshlrev_b32_e32 v2, 16, v183
	v_and_b32_e32 v4, 0xffff0000, v183
	v_mul_f32_e32 v2, v96, v2
	v_mul_f32_e32 v4, v97, v4
	v_cvt_pk_bf16_f32 v101, v2, v4
	v_lshlrev_b32_e32 v2, 16, v184
	v_and_b32_e32 v4, 0xffff0000, v184
	v_mul_f32_e32 v2, v90, v2
	v_mul_f32_e32 v4, v91, v4
	global_store_dwordx4 v165, v[98:101], s[16:17] sc0 sc1
	v_cvt_pk_bf16_f32 v90, v2, v4
	v_lshlrev_b32_e32 v2, 16, v185
	v_and_b32_e32 v4, 0xffff0000, v185
	v_mul_f32_e32 v2, v92, v2
	v_mul_f32_e32 v4, v93, v4
	v_cvt_pk_bf16_f32 v91, v2, v4
	v_lshlrev_b32_e32 v2, 16, v186
	v_and_b32_e32 v4, 0xffff0000, v186
	v_mul_f32_e32 v2, v86, v2
	v_mul_f32_e32 v4, v87, v4
	v_cvt_pk_bf16_f32 v92, v2, v4
	v_lshlrev_b32_e32 v2, 16, v187
	v_and_b32_e32 v4, 0xffff0000, v187
	v_mul_f32_e32 v2, v88, v2
	v_mul_f32_e32 v4, v89, v4
	v_cvt_pk_bf16_f32 v93, v2, v4
	v_lshlrev_b32_e32 v2, 16, v188
	v_and_b32_e32 v4, 0xffff0000, v188
	v_mul_f32_e32 v2, v82, v2
	v_mul_f32_e32 v4, v83, v4
	global_store_dwordx4 v166, v[90:93], s[16:17] sc0 sc1
	v_cvt_pk_bf16_f32 v82, v2, v4
	v_lshlrev_b32_e32 v2, 16, v189
	v_and_b32_e32 v4, 0xffff0000, v189
	v_mul_f32_e32 v2, v84, v2
	v_mul_f32_e32 v4, v85, v4
	v_cvt_pk_bf16_f32 v83, v2, v4
	v_lshlrev_b32_e32 v2, 16, v190
	v_and_b32_e32 v4, 0xffff0000, v190
	v_mul_f32_e32 v2, v78, v2
	v_mul_f32_e32 v4, v79, v4
	v_cvt_pk_bf16_f32 v84, v2, v4
	v_lshlrev_b32_e32 v2, 16, v191
	v_and_b32_e32 v4, 0xffff0000, v191
	v_mul_f32_e32 v2, v80, v2
	v_mul_f32_e32 v4, v81, v4
	v_cvt_pk_bf16_f32 v85, v2, v4
	v_lshlrev_b32_e32 v2, 16, v192
	v_and_b32_e32 v4, 0xffff0000, v192
	v_mul_f32_e32 v2, v74, v2
	v_mul_f32_e32 v4, v75, v4
	global_store_dwordx4 v167, v[82:85], s[16:17] sc0 sc1
	v_cvt_pk_bf16_f32 v74, v2, v4
	v_lshlrev_b32_e32 v2, 16, v193
	v_and_b32_e32 v4, 0xffff0000, v193
	v_mul_f32_e32 v2, v76, v2
	v_mul_f32_e32 v4, v77, v4
	v_cvt_pk_bf16_f32 v75, v2, v4
	v_lshlrev_b32_e32 v2, 16, v194
	v_and_b32_e32 v4, 0xffff0000, v194
	v_mul_f32_e32 v2, v70, v2
	v_mul_f32_e32 v4, v71, v4
	v_cvt_pk_bf16_f32 v76, v2, v4
	v_lshlrev_b32_e32 v2, 16, v195
	v_and_b32_e32 v4, 0xffff0000, v195
	v_mul_f32_e32 v2, v72, v2
	v_mul_f32_e32 v4, v73, v4
	v_cvt_pk_bf16_f32 v77, v2, v4
	global_store_dwordx4 v196, v[74:77], s[16:17] sc0 sc1
	v_add_u32_e32 v2, 0x80000, v164
	global_load_dwordx4 v[70:73], v2, s[2:3]
	v_add_u32_e32 v4, 0x80100, v164
	global_load_dwordx4 v[74:77], v4, s[2:3]
	v_add_u32_e32 v5, 0x90000, v164
	global_load_dwordx4 v[78:81], v5, s[2:3]
	v_add_u32_e32 v102, 0x90100, v164
	global_load_dwordx4 v[82:85], v102, s[2:3]
	v_add_u32_e32 v103, 0xa0000, v164
	v_add_u32_e32 v104, 0xa0100, v164
	global_load_dwordx4 v[86:89], v103, s[2:3]
	global_load_dwordx4 v[90:93], v104, s[2:3]
	v_add_u32_e32 v105, 0xb0000, v164
	v_add_u32_e32 v106, 0xb0100, v164
	global_load_dwordx4 v[94:97], v105, s[2:3]
	global_load_dwordx4 v[98:101], v106, s[2:3]
	s_waitcnt vmcnt(7)
	v_lshlrev_b32_e32 v107, 16, v70
	v_and_b32_e32 v70, 0xffff0000, v70
	v_mul_f32_e32 v66, v66, v107
	v_mul_f32_e32 v67, v67, v70
	v_cvt_pk_bf16_f32 v66, v66, v67
	v_lshlrev_b32_e32 v67, 16, v71
	v_mul_f32_e32 v67, v68, v67
	v_and_b32_e32 v68, 0xffff0000, v71
	v_mul_f32_e32 v68, v69, v68
	v_cvt_pk_bf16_f32 v67, v67, v68
	v_lshlrev_b32_e32 v68, 16, v72
	v_mul_f32_e32 v62, v62, v68
	v_and_b32_e32 v68, 0xffff0000, v72
	v_mul_f32_e32 v63, v63, v68
	v_cvt_pk_bf16_f32 v68, v62, v63
	v_lshlrev_b32_e32 v62, 16, v73
	v_and_b32_e32 v63, 0xffff0000, v73
	v_mul_f32_e32 v62, v64, v62
	v_mul_f32_e32 v63, v65, v63
	v_cvt_pk_bf16_f32 v69, v62, v63
	global_store_dwordx4 v2, v[66:69], s[16:17] sc0 sc1
	s_waitcnt vmcnt(7)
	v_lshlrev_b32_e32 v2, 16, v74
	v_mul_f32_e32 v2, v58, v2
	v_and_b32_e32 v58, 0xffff0000, v74
	v_mul_f32_e32 v58, v59, v58
	v_cvt_pk_bf16_f32 v58, v2, v58
	v_lshlrev_b32_e32 v2, 16, v75
	v_and_b32_e32 v59, 0xffff0000, v75
	v_mul_f32_e32 v2, v60, v2
	v_mul_f32_e32 v59, v61, v59
	v_cvt_pk_bf16_f32 v59, v2, v59
	v_lshlrev_b32_e32 v2, 16, v76
	v_mul_f32_e32 v2, v54, v2
	v_and_b32_e32 v54, 0xffff0000, v76
	v_mul_f32_e32 v54, v55, v54
	v_cvt_pk_bf16_f32 v60, v2, v54
	v_lshlrev_b32_e32 v2, 16, v77
	v_mul_f32_e32 v2, v56, v2
	v_and_b32_e32 v54, 0xffff0000, v77
	v_mul_f32_e32 v54, v57, v54
	v_cvt_pk_bf16_f32 v61, v2, v54
	global_store_dwordx4 v4, v[58:61], s[16:17] sc0 sc1
	s_waitcnt vmcnt(7)
	v_lshlrev_b32_e32 v2, 16, v78
	v_and_b32_e32 v4, 0xffff0000, v78
	v_mul_f32_e32 v2, v50, v2
	v_mul_f32_e32 v4, v51, v4
	v_cvt_pk_bf16_f32 v50, v2, v4
	v_lshlrev_b32_e32 v2, 16, v79
	v_and_b32_e32 v4, 0xffff0000, v79
	v_mul_f32_e32 v2, v52, v2
	v_mul_f32_e32 v4, v53, v4
	v_cvt_pk_bf16_f32 v51, v2, v4
	v_lshlrev_b32_e32 v2, 16, v80
	v_and_b32_e32 v4, 0xffff0000, v80
	v_mul_f32_e32 v2, v46, v2
	v_mul_f32_e32 v4, v47, v4
	v_cvt_pk_bf16_f32 v52, v2, v4
	v_lshlrev_b32_e32 v2, 16, v81
	v_and_b32_e32 v4, 0xffff0000, v81
	v_mul_f32_e32 v2, v48, v2
	v_mul_f32_e32 v4, v49, v4
	v_cvt_pk_bf16_f32 v53, v2, v4
	s_waitcnt vmcnt(6)
	v_lshlrev_b32_e32 v2, 16, v82
	v_and_b32_e32 v4, 0xffff0000, v82
	v_mul_f32_e32 v2, v42, v2
	v_mul_f32_e32 v4, v43, v4
	global_store_dwordx4 v5, v[50:53], s[16:17] sc0 sc1
	v_cvt_pk_bf16_f32 v42, v2, v4
	v_lshlrev_b32_e32 v2, 16, v83
	v_and_b32_e32 v4, 0xffff0000, v83
	v_mul_f32_e32 v2, v44, v2
	v_mul_f32_e32 v4, v45, v4
	v_cvt_pk_bf16_f32 v43, v2, v4
	v_lshlrev_b32_e32 v2, 16, v84
	v_and_b32_e32 v4, 0xffff0000, v84
	v_mul_f32_e32 v2, v38, v2
	v_mul_f32_e32 v4, v39, v4
	v_cvt_pk_bf16_f32 v44, v2, v4
	v_lshlrev_b32_e32 v2, 16, v85
	v_and_b32_e32 v4, 0xffff0000, v85
	v_mul_f32_e32 v2, v40, v2
	v_mul_f32_e32 v4, v41, v4
	v_cvt_pk_bf16_f32 v45, v2, v4
	s_waitcnt vmcnt(6)
	v_lshlrev_b32_e32 v2, 16, v86
	v_and_b32_e32 v4, 0xffff0000, v86
	v_mul_f32_e32 v2, v34, v2
	v_mul_f32_e32 v4, v35, v4
	global_store_dwordx4 v102, v[42:45], s[16:17] sc0 sc1
	v_cvt_pk_bf16_f32 v34, v2, v4
	v_lshlrev_b32_e32 v2, 16, v87
	v_and_b32_e32 v4, 0xffff0000, v87
	v_mul_f32_e32 v2, v36, v2
	v_mul_f32_e32 v4, v37, v4
	v_cvt_pk_bf16_f32 v35, v2, v4
	v_lshlrev_b32_e32 v2, 16, v88
	v_and_b32_e32 v4, 0xffff0000, v88
	v_mul_f32_e32 v2, v30, v2
	v_mul_f32_e32 v4, v31, v4
	v_cvt_pk_bf16_f32 v36, v2, v4
	v_lshlrev_b32_e32 v2, 16, v89
	v_and_b32_e32 v4, 0xffff0000, v89
	v_mul_f32_e32 v2, v32, v2
	v_mul_f32_e32 v4, v33, v4
	v_cvt_pk_bf16_f32 v37, v2, v4
	s_waitcnt vmcnt(6)
	v_lshlrev_b32_e32 v2, 16, v90
	v_and_b32_e32 v4, 0xffff0000, v90
	v_mul_f32_e32 v2, v26, v2
	v_mul_f32_e32 v4, v27, v4
	global_store_dwordx4 v103, v[34:37], s[16:17] sc0 sc1
	v_cvt_pk_bf16_f32 v26, v2, v4
	v_lshlrev_b32_e32 v2, 16, v91
	v_and_b32_e32 v4, 0xffff0000, v91
	v_mul_f32_e32 v2, v28, v2
	v_mul_f32_e32 v4, v29, v4
	v_cvt_pk_bf16_f32 v27, v2, v4
	v_lshlrev_b32_e32 v2, 16, v92
	v_and_b32_e32 v4, 0xffff0000, v92
	v_mul_f32_e32 v2, v22, v2
	v_mul_f32_e32 v4, v23, v4
	v_cvt_pk_bf16_f32 v28, v2, v4
	v_lshlrev_b32_e32 v2, 16, v93
	v_and_b32_e32 v4, 0xffff0000, v93
	v_mul_f32_e32 v2, v24, v2
	v_mul_f32_e32 v4, v25, v4
	v_cvt_pk_bf16_f32 v29, v2, v4
	s_waitcnt vmcnt(6)
	v_lshlrev_b32_e32 v2, 16, v94
	v_and_b32_e32 v4, 0xffff0000, v94
	v_mul_f32_e32 v2, v18, v2
	v_mul_f32_e32 v4, v19, v4
	global_store_dwordx4 v104, v[26:29], s[16:17] sc0 sc1
	v_cvt_pk_bf16_f32 v18, v2, v4
	v_lshlrev_b32_e32 v2, 16, v95
	v_and_b32_e32 v4, 0xffff0000, v95
	v_mul_f32_e32 v2, v20, v2
	v_mul_f32_e32 v4, v21, v4
	v_cvt_pk_bf16_f32 v19, v2, v4
	v_lshlrev_b32_e32 v2, 16, v96
	v_and_b32_e32 v4, 0xffff0000, v96
	v_mul_f32_e32 v2, v14, v2
	v_mul_f32_e32 v4, v15, v4
	v_cvt_pk_bf16_f32 v20, v2, v4
	v_lshlrev_b32_e32 v2, 16, v97
	v_and_b32_e32 v4, 0xffff0000, v97
	v_mul_f32_e32 v2, v16, v2
	v_mul_f32_e32 v4, v17, v4
	v_cvt_pk_bf16_f32 v21, v2, v4
	s_waitcnt vmcnt(6)
	v_lshlrev_b32_e32 v2, 16, v98
	v_and_b32_e32 v4, 0xffff0000, v98
	v_mul_f32_e32 v2, v10, v2
	v_mul_f32_e32 v4, v11, v4
	global_store_dwordx4 v105, v[18:21], s[16:17] sc0 sc1
	v_cvt_pk_bf16_f32 v4, v2, v4
	v_lshlrev_b32_e32 v2, 16, v99
	v_and_b32_e32 v5, 0xffff0000, v99
	v_mul_f32_e32 v2, v12, v2
	v_mul_f32_e32 v5, v13, v5
	v_cvt_pk_bf16_f32 v5, v2, v5
	v_lshlrev_b32_e32 v2, 16, v100
	v_mul_f32_e32 v2, v6, v2
	v_and_b32_e32 v6, 0xffff0000, v100
	v_mul_f32_e32 v6, v7, v6
	v_and_b32_e32 v7, 0xffff0000, v101
	v_cvt_pk_bf16_f32 v6, v2, v6
	v_lshlrev_b32_e32 v2, 16, v101
	v_mul_f32_e32 v7, v9, v7
	v_mul_f32_e32 v2, v8, v2
	v_cvt_pk_bf16_f32 v7, v2, v7
	global_store_dwordx4 v106, v[4:7], s[16:17] sc0 sc1
	s_mov_b64 s[16:17], -1
	s_branch .Ljoin_mrg
